# phase_tail gate loop: removed unreachable denormal/inf handling of log(1+e), e in [0,1] (bit-identical)
# speedup vs baseline: 1.0079x; 1.0079x over previous
.LBB0_229:
	ds_read_b128 v[42:45], v40
	ds_read_b128 v[46:49], v40 offset:16
	ds_read_b128 v[50:53], v40 offset:32
	ds_read_b128 v[54:57], v40 offset:48
	ds_read_b128 v[58:61], v40 offset:144
	ds_read_b128 v[62:65], v40 offset:160
	ds_read_b128 v[66:69], v40 offset:176
	ds_read_b128 v[70:73], v40 offset:192
	ds_read_b128 v[74:77], v40 offset:288
	ds_read_b128 v[78:81], v40 offset:304
	ds_read_b128 v[82:85], v40 offset:320
	ds_read_b128 v[86:89], v40 offset:336
	ds_read_b128 v[90:93], v40 offset:432
	ds_read_b128 v[94:97], v40 offset:448
	ds_read_b128 v[98:101], v40 offset:464
	ds_read_b128 v[102:105], v40 offset:480
	s_waitcnt lgkmcnt(14)
	v_pk_mul_f32 v[44:45], v[10:11], v[44:45]
	v_pk_mul_f32 v[48:49], v[12:13], v[48:49]
	s_waitcnt lgkmcnt(11)
	v_pk_mul_f32 v[60:61], v[10:11], v[60:61]
	s_waitcnt lgkmcnt(10)
	v_pk_mul_f32 v[64:65], v[12:13], v[64:65]
	s_waitcnt lgkmcnt(7)
	v_pk_mul_f32 v[76:77], v[10:11], v[76:77]
	s_waitcnt lgkmcnt(6)
	v_pk_mul_f32 v[80:81], v[12:13], v[80:81]
	s_waitcnt lgkmcnt(3)
	v_pk_mul_f32 v[92:93], v[10:11], v[92:93]
	s_waitcnt lgkmcnt(2)
	v_pk_mul_f32 v[96:97], v[12:13], v[96:97]
	v_pk_fma_f32 v[42:43], v[8:9], v[42:43], v[44:45]
	v_pk_fma_f32 v[44:45], v[2:3], v[46:47], v[48:49]
	v_pk_fma_f32 v[46:47], v[8:9], v[58:59], v[60:61]
	v_pk_fma_f32 v[48:49], v[2:3], v[62:63], v[64:65]
	v_pk_fma_f32 v[58:59], v[8:9], v[74:75], v[76:77]
	v_pk_fma_f32 v[60:61], v[2:3], v[78:79], v[80:81]
	v_pk_fma_f32 v[62:63], v[8:9], v[90:91], v[92:93]
	v_pk_fma_f32 v[64:65], v[2:3], v[94:95], v[96:97]
	v_pk_fma_f32 v[42:43], v[4:5], v[50:51], v[42:43]
	v_pk_fma_f32 v[44:45], v[14:15], v[54:55], v[44:45]
	v_pk_fma_f32 v[46:47], v[4:5], v[66:67], v[46:47]
	v_pk_fma_f32 v[48:49], v[14:15], v[70:71], v[48:49]
	v_pk_fma_f32 v[50:51], v[4:5], v[82:83], v[58:59]
	v_pk_fma_f32 v[54:55], v[14:15], v[86:87], v[60:61]
	s_waitcnt lgkmcnt(1)
	v_pk_fma_f32 v[58:59], v[4:5], v[98:99], v[62:63]
	s_waitcnt lgkmcnt(0)
	v_pk_fma_f32 v[60:61], v[14:15], v[102:103], v[64:65]
	v_pk_fma_f32 v[42:43], v[6:7], v[52:53], v[42:43]
	v_pk_fma_f32 v[44:45], v[16:17], v[56:57], v[44:45]
	v_pk_fma_f32 v[46:47], v[6:7], v[68:69], v[46:47]
	v_pk_fma_f32 v[48:49], v[16:17], v[72:73], v[48:49]
	v_pk_fma_f32 v[50:51], v[6:7], v[84:85], v[50:51]
	v_pk_fma_f32 v[52:53], v[16:17], v[88:89], v[54:55]
	v_pk_fma_f32 v[54:55], v[6:7], v[100:101], v[58:59]
	v_pk_fma_f32 v[56:57], v[16:17], v[104:105], v[60:61]
	v_pk_add_f32 v[42:43], v[42:43], v[44:45]
	v_pk_add_f32 v[44:45], v[46:47], v[48:49]
	v_pk_add_f32 v[46:47], v[50:51], v[52:53]
	v_pk_add_f32 v[48:49], v[54:55], v[56:57]
	v_add_f32_e32 v41, v42, v43
	v_add_f32_e32 v42, v44, v45
	v_add_f32_e32 v43, v46, v47
	v_add_f32_e32 v44, v48, v49
	v_add_f32_e32 v41, v33, v41
	v_add_f32_e32 v42, v33, v42
	v_add_f32_e32 v43, v33, v43
	v_add_f32_e32 v44, v33, v44
	v_min_f32_e32 v45, 0, v41
	v_mul_f32_e64 v41, |v41|, s13
	v_min_f32_e32 v46, 0, v42
	v_mul_f32_e64 v42, |v42|, s13
	v_min_f32_e32 v47, 0, v43
	v_mul_f32_e64 v43, |v43|, s13
	v_min_f32_e32 v48, 0, v44
	v_mul_f32_e64 v44, |v44|, s13
	v_exp_f32_e32 v41, v41
	v_exp_f32_e32 v42, v42
	v_exp_f32_e32 v43, v43
	v_exp_f32_e32 v44, v44
	s_add_i32 s4, s10, s28
	s_ashr_i32 s5, s4, 31
	s_add_i32 s6, s4, 1
	s_add_i32 s8, s4, 2
	s_add_i32 s56, s4, 3
	s_lshl_b64 s[4:5], s[4:5], 10
	s_ashr_i32 s7, s6, 31
	s_ashr_i32 s9, s8, 31
	s_ashr_i32 s57, s56, 31
	v_add_f32_e32 v41, 1.0, v41
	v_lshl_add_u64 v[106:107], v[24:25], 0, s[4:5]
	s_lshl_b64 s[4:5], s[6:7], 10
	s_lshl_b64 s[6:7], s[8:9], 10
	s_lshl_b64 s[8:9], s[56:57], 10
	v_add_f32_e32 v42, 1.0, v42
	v_add_f32_e32 v43, 1.0, v43
	v_add_f32_e32 v44, 1.0, v44
	v_lshl_add_u64 v[108:109], v[24:25], 0, s[4:5]
	v_lshl_add_u64 v[110:111], v[24:25], 0, s[6:7]
	v_lshl_add_u64 v[112:113], v[24:25], 0, s[8:9]
	v_log_f32_e32 v41, v41
	v_log_f32_e32 v42, v42
	v_log_f32_e32 v43, v43
	v_log_f32_e32 v44, v44
	v_mul_f32_e32 v53, 0x3f317217, v41
	v_mul_f32_e32 v54, 0x3f317217, v42
	v_mul_f32_e32 v55, 0x3f317217, v43
	v_mul_f32_e32 v56, 0x3f317217, v44
	v_fma_f32 v53, v41, s15, -v53
	v_fma_f32 v54, v42, s15, -v54
	v_fma_f32 v55, v43, s15, -v55
	v_fma_f32 v56, v44, s15, -v56
	v_fmac_f32_e32 v53, 0x3377d1cf, v41
	v_fmac_f32_e32 v54, 0x3377d1cf, v42
	v_fmac_f32_e32 v55, 0x3377d1cf, v43
	v_fmac_f32_e32 v56, 0x3377d1cf, v44
	v_fmac_f32_e32 v53, 0x3f317217, v41
	v_fmac_f32_e32 v54, 0x3f317217, v42
	v_fmac_f32_e32 v55, 0x3f317217, v43
	v_fmac_f32_e32 v56, 0x3f317217, v44
	s_add_i32 s28, s28, 4
	v_sub_f32_e32 v41, v45, v53
	v_add_u32_e32 v40, 0x240, v40
	s_cmp_eq_u32 s28, 48
	v_sub_f32_e32 v42, v46, v54
	v_sub_f32_e32 v43, v47, v55
	v_sub_f32_e32 v44, v48, v56
	v_fma_mixlo_f16 v41, v41, s17, 0
	v_fma_mixlo_f16 v42, v42, s17, 0
	v_fma_mixlo_f16 v43, v43, s17, 0
	v_fma_mixlo_f16 v44, v44, s17, 0
	global_store_short v[106:107], v41, off
	global_store_short v[108:109], v42, off
	global_store_short v[110:111], v43, off
	global_store_short v[112:113], v44, off
	s_cbranch_scc0 .LBB0_229
	s_add_i32 s19, s19, s26
	s_add_i32 s10, s10, s34
	s_cmpk_gt_i32 s19, 0xff
	s_barrier
	s_cbranch_scc0 .LBB0_225
